# mlstmA K^T LDS tile XOR-swizzled (16B chunk ^= (row>>3)&7): transposing ds_write_b16 stores spread over 16 banks instead of 4
# speedup vs baseline: 1.0038x; 1.0010x over previous
; DI u16 f2bf(float x) { return (u16)(pack2(x, 0.f) & 0xffffu); }
; DI void conv_unit(const u16* __restrict__ PM, const float* __restrict__ conv_w, const float* __restrict__ conv_b, int b, int sl0, int ch, float scale, float* a8) {
;   { const float4 b0 = *(const float4*)(conv_b + ch), b1 = *(const float4*)(conv_b + ch + 4); a8[0] = b0.x; a8[1] = b0.y; a8[2] = b0.z; a8[3] = b0.w; a8[4] = b1.x; a8[5] = b1.y; a8[6] = b1.z; a8[7] = b1.w; }
; #pragma unroll
;   for (int j = 0; j < 4; ++j) {
;     const int sl = sl0 - 3 + j;
;     if (sl >= 0) {
;       const uint4 raw = *(const uint4*)(PM + ((size_t)b * SEQ + sl) * 1024 + ch);
;       float x8[8]; unpack8(raw, x8);
;       const float4 w0 = *(const float4*)(conv_w + j * 1024 + ch), w1 = *(const float4*)(conv_w + j * 1024 + ch + 4);
;       a8[0] += w0.x * x8[0]; a8[1] += w0.y * x8[1]; a8[2] += w0.z * x8[2]; a8[3] += w0.w * x8[3];
;       a8[4] += w1.x * x8[4]; a8[5] += w1.y * x8[5]; a8[6] += w1.z * x8[6]; a8[7] += w1.w * x8[7];
;     }
;   }
; #pragma unroll
;   for (int e = 0; e < 8; ++e) { const float v = a8[e]; a8[e] = scale * v * __builtin_amdgcn_rcpf(1.f + __expf(-v)); }
; }
; DI void mlstmA_item(const Params& p, char* lds, int item) {
;     ...
;   for (int i = 0; i < 2; ++i) {
;     const int q = tid + 512 * i, e = q >> 3, s8 = (q & 7) * 8;
;     *(uint4*)(VTs + e * 72 + s8) = *(const uint4*)(VTm + ((size_t)(bh * 128 + e)) * SEQ + c * 64 + s8);
;   }
;   __syncthreads();
; #pragma unroll 1
;   for (int i = 0; i < 2; ++i) {
;     const int cgk = tid & 15, t = (tid >> 4) + 32 * i;
;     float a8[8];
;     conv_unit(PM, p.in[5], p.in[6], b, c * 64 + t, 512 + hd * 128 + cgk * 8, 0.08838834764831845f, a8);
;     const float w = win[t];
; #pragma unroll
;     for (int e = 0; e < 8; ++e) KTs[(cgk * 8 + e) * 72 + t] = f2bf(a8[e] * w);
;   }
.LBB0_330:
	s_or_b64 exec, exec, s[14:15]
	v_add_u32_e32 v4, 0x200, v18
	s_and_b32 s0, s10, 0xffffff80
	v_lshlrev_b32_e32 v2, 4, v18
	v_ashrrev_i32_e32 v9, 3, v18
	v_ashrrev_i32_e32 v14, 3, v4
	v_and_b32_e32 v16, 0x70, v2
	v_add_u32_e32 v2, s0, v9
	v_add_u32_e32 v4, s0, v14
	v_lshl_add_u64 v[0:1], v[0:1], 1, s[6:7]
	v_ashrrev_i32_e32 v3, 31, v2
	v_ashrrev_i32_e32 v5, 31, v4
	v_lshl_add_u64 v[0:1], v[0:1], 0, v[16:17]
	v_lshlrev_b64 v[2:3], 14, v[2:3]
	v_lshlrev_b64 v[4:5], 14, v[4:5]
	v_lshl_add_u64 v[2:3], v[0:1], 0, v[2:3]
	v_lshl_add_u64 v[4:5], v[0:1], 0, v[4:5]
	v_lshlrev_b32_e32 v8, 3, v18
	v_and_b32_e32 v22, 0x78, v8
	v_add_u32_e32 v8, 0, v16
	v_lshl_or_b32 v15, s27, 7, v22
	v_mad_u64_u32 v[12:13], s[0:1], v9, s26, v[8:9]
	v_lshlrev_b32_e32 v16, 2, v15
	v_mad_u64_u32 v[8:9], s[0:1], v14, s26, v[8:9]
	v_lshlrev_b64 v[10:11], 24, v[10:11]
	v_lshl_add_u64 v[10:11], s[4:5], 0, v[10:11]
	v_mov_b32_e32 v13, v17
	s_mov_b64 s[0:1], 0x1800
	v_ashrrev_i32_e32 v51, 4, v18
	v_mad_u32_u24 v52, v22, s26, 0
	s_mov_b32 s8, 0
	s_waitcnt vmcnt(20)
	ds_write_b128 v12, v[232:235] offset:18432
	ds_write_b128 v8, v[236:239] offset:18432
	s_waitcnt lgkmcnt(0)
	s_barrier
	s_add_i32 s97, s10, s70
	v_add_u32_e32 v240, 0x200, v222
	s_and_b32 s73, s97, 0xffffff80
	v_lshlrev_b32_e32 v241, 4, v222
	v_ashrrev_i32_e32 v242, 3, v222
	v_ashrrev_i32_e32 v244, 3, v240
	v_and_b32_e32 v246, 0x70, v241
	v_mov_b32_e32 v247, 0
	v_add_u32_e32 v242, s73, v242
	v_add_u32_e32 v244, s73, v244
	s_and_b32 s78, s97, 0x7f
	s_lshl_b32 s78, s78, 7
	v_mov_b32_e32 v248, s78
	v_mov_b32_e32 v249, 0
	v_lshl_add_u64 v[248:249], s[6:7], 0, v[248:249]
	v_lshl_add_u64 v[248:249], v[248:249], 0, v[246:247]
	v_ashrrev_i32_e32 v243, 31, v242
	v_ashrrev_i32_e32 v245, 31, v244
	v_lshlrev_b64 v[242:243], 14, v[242:243]
	v_lshlrev_b64 v[244:245], 14, v[244:245]
	v_lshl_add_u64 v[242:243], v[248:249], 0, v[242:243]
	v_lshl_add_u64 v[244:245], v[248:249], 0, v[244:245]
	global_load_dwordx4 v[232:235], v[242:243], off
	global_load_dwordx4 v[236:239], v[244:245], off
	s_waitcnt vmcnt(2)
	v_mov_b32_e32 v197, v51
	v_lshl_add_u32 v196, v197, 2, s96
	ds_read_b32 v196, v196 offset:40960
	v_lshrrev_b32_e32 v199, 3, v197
	v_and_b32_e32 v200, 7, v222
	v_xor_b32_e32 v199, v199, v200
	v_and_b32_e32 v200, 7, v197
	v_lshlrev_b32_e32 v200, 1, v200
	v_lshl_or_b32 v199, v199, 4, v200
	v_add_u32_e32 v198, v52, v199
	v_lshlrev_b32_e32 v188, 16, v114
	v_and_b32_e32 v189, 0xffff0000, v114
	v_lshlrev_b32_e32 v190, 16, v115
	v_and_b32_e32 v191, 0xffff0000, v115
	v_lshlrev_b32_e32 v192, 16, v116
	v_and_b32_e32 v193, 0xffff0000, v116
	v_lshlrev_b32_e32 v194, 16, v117
	v_and_b32_e32 v195, 0xffff0000, v117
	v_pk_fma_f32 v[204:205], v[140:141], v[188:189], v[224:225]
	v_pk_fma_f32 v[206:207], v[142:143], v[190:191], v[226:227]
	v_pk_fma_f32 v[208:209], v[144:145], v[192:193], v[228:229]
	v_pk_fma_f32 v[210:211], v[146:147], v[194:195], v[230:231]
	v_lshlrev_b32_e32 v188, 16, v118
	v_and_b32_e32 v189, 0xffff0000, v118
	v_lshlrev_b32_e32 v190, 16, v119
	v_and_b32_e32 v191, 0xffff0000, v119
	v_lshlrev_b32_e32 v192, 16, v120
	v_and_b32_e32 v193, 0xffff0000, v120
	v_lshlrev_b32_e32 v194, 16, v121
	v_and_b32_e32 v195, 0xffff0000, v121
	v_pk_fma_f32 v[204:205], v[148:149], v[188:189], v[204:205]
	v_pk_fma_f32 v[206:207], v[150:151], v[190:191], v[206:207]
	v_pk_fma_f32 v[208:209], v[152:153], v[192:193], v[208:209]
	v_pk_fma_f32 v[210:211], v[154:155], v[194:195], v[210:211]
	v_lshlrev_b32_e32 v188, 16, v122
	v_and_b32_e32 v189, 0xffff0000, v122
	v_lshlrev_b32_e32 v190, 16, v123
	v_and_b32_e32 v191, 0xffff0000, v123
	v_lshlrev_b32_e32 v192, 16, v124
	v_and_b32_e32 v193, 0xffff0000, v124
	v_lshlrev_b32_e32 v194, 16, v125
	v_and_b32_e32 v195, 0xffff0000, v125
	v_pk_fma_f32 v[204:205], v[156:157], v[188:189], v[204:205]
	v_pk_fma_f32 v[206:207], v[158:159], v[190:191], v[206:207]
	v_pk_fma_f32 v[208:209], v[160:161], v[192:193], v[208:209]
	v_pk_fma_f32 v[210:211], v[162:163], v[194:195], v[210:211]
	v_lshlrev_b32_e32 v188, 16, v126
	v_and_b32_e32 v189, 0xffff0000, v126
	v_lshlrev_b32_e32 v190, 16, v127
	v_and_b32_e32 v191, 0xffff0000, v127
	v_lshlrev_b32_e32 v192, 16, v128
	v_and_b32_e32 v193, 0xffff0000, v128
	v_lshlrev_b32_e32 v194, 16, v129
	v_and_b32_e32 v195, 0xffff0000, v129
	v_pk_fma_f32 v[204:205], v[164:165], v[188:189], v[204:205]
	v_pk_fma_f32 v[206:207], v[166:167], v[190:191], v[206:207]
	v_pk_fma_f32 v[208:209], v[168:169], v[192:193], v[208:209]
	v_pk_fma_f32 v[210:211], v[170:171], v[194:195], v[210:211]
	v_mul_f32_e32 v212, 0xbfb8aa3b, v204
	v_mul_f32_e32 v213, 0xbfb8aa3b, v205
	v_mul_f32_e32 v214, 0xbfb8aa3b, v206
	v_mul_f32_e32 v215, 0xbfb8aa3b, v207
	v_mul_f32_e32 v216, 0xbfb8aa3b, v208
	v_mul_f32_e32 v217, 0xbfb8aa3b, v209
	v_mul_f32_e32 v218, 0xbfb8aa3b, v210
	v_mul_f32_e32 v219, 0xbfb8aa3b, v211
	v_mul_f32_e32 v188, 0x3db504f3, v204
	v_mul_f32_e32 v189, 0x3db504f3, v205
	v_mul_f32_e32 v190, 0x3db504f3, v206
	v_mul_f32_e32 v191, 0x3db504f3, v207
	v_mul_f32_e32 v192, 0x3db504f3, v208
	v_mul_f32_e32 v193, 0x3db504f3, v209
	v_mul_f32_e32 v194, 0x3db504f3, v210
	v_mul_f32_e32 v195, 0x3db504f3, v211
	v_exp_f32_e32 v212, v212
	v_exp_f32_e32 v213, v213
	v_exp_f32_e32 v214, v214
	v_exp_f32_e32 v215, v215
	v_exp_f32_e32 v216, v216
	v_exp_f32_e32 v217, v217
	v_exp_f32_e32 v218, v218
	v_exp_f32_e32 v219, v219
	v_add_f32_e32 v212, 1.0, v212
	v_add_f32_e32 v213, 1.0, v213
	v_add_f32_e32 v214, 1.0, v214
	v_add_f32_e32 v215, 1.0, v215
	v_add_f32_e32 v216, 1.0, v216
	v_add_f32_e32 v217, 1.0, v217
	v_add_f32_e32 v218, 1.0, v218
	v_add_f32_e32 v219, 1.0, v219
	v_rcp_f32_e32 v212, v212
	v_rcp_f32_e32 v213, v213
	v_rcp_f32_e32 v214, v214
	v_rcp_f32_e32 v215, v215
	v_rcp_f32_e32 v216, v216
	v_rcp_f32_e32 v217, v217
	v_rcp_f32_e32 v218, v218
	v_rcp_f32_e32 v219, v219
	v_mul_f32_e32 v188, v188, v212
	v_mul_f32_e32 v189, v189, v213
	v_mul_f32_e32 v190, v190, v214
	v_mul_f32_e32 v191, v191, v215
	v_mul_f32_e32 v192, v192, v216
	v_mul_f32_e32 v193, v193, v217
	v_mul_f32_e32 v194, v194, v218
	v_mul_f32_e32 v195, v195, v219
	s_waitcnt lgkmcnt(0)
; DI u16 f2bf(float x) { return (u16)(pack2(x, 0.f) & 0xffffu); }
; DI void conv_unit(const u16* __restrict__ PM, const float* __restrict__ conv_w, const float* __restrict__ conv_b, int b, int sl0, int ch, float scale, float* a8) {
;   { const float4 b0 = *(const float4*)(conv_b + ch), b1 = *(const float4*)(conv_b + ch + 4); a8[0] = b0.x; a8[1] = b0.y; a8[2] = b0.z; a8[3] = b0.w; a8[4] = b1.x; a8[5] = b1.y; a8[6] = b1.z; a8[7] = b1.w; }
; #pragma unroll
;   for (int j = 0; j < 4; ++j) {
;     const int sl = sl0 - 3 + j;
;     if (sl >= 0) {
;       const uint4 raw = *(const uint4*)(PM + ((size_t)b * SEQ + sl) * 1024 + ch);
;       float x8[8]; unpack8(raw, x8);
;       const float4 w0 = *(const float4*)(conv_w + j * 1024 + ch), w1 = *(const float4*)(conv_w + j * 1024 + ch + 4);
;       a8[0] += w0.x * x8[0]; a8[1] += w0.y * x8[1]; a8[2] += w0.z * x8[2]; a8[3] += w0.w * x8[3];
;       a8[4] += w1.x * x8[4]; a8[5] += w1.y * x8[5]; a8[6] += w1.z * x8[6]; a8[7] += w1.w * x8[7];
;     }
;   }
; #pragma unroll
;   for (int e = 0; e < 8; ++e) { const float v = a8[e]; a8[e] = scale * v * __builtin_amdgcn_rcpf(1.f + __expf(-v)); }
; }
; DI void mlstmA_item(const Params& p, char* lds, int item) {
;     ...
;   for (int i = 0; i < 2; ++i) {
;     const int q = tid + 512 * i, e = q >> 3, s8 = (q & 7) * 8;
;     *(uint4*)(VTs + e * 72 + s8) = *(const uint4*)(VTm + ((size_t)(bh * 128 + e)) * SEQ + c * 64 + s8);
;   }
;   __syncthreads();
; #pragma unroll 1
;   for (int i = 0; i < 2; ++i) {
;     const int cgk = tid & 15, t = (tid >> 4) + 32 * i;
;     float a8[8];
;     conv_unit(PM, p.in[5], p.in[6], b, c * 64 + t, 512 + hd * 128 + cgk * 8, 0.08838834764831845f, a8);
;     const float w = win[t];
; #pragma unroll
;     for (int e = 0; e < 8; ++e) KTs[(cgk * 8 + e) * 72 + t] = f2bf(a8[e] * w);
;   }
	v_mul_f32_e32 v188, v196, v188
	v_mul_f32_e32 v189, v196, v189
	v_mul_f32_e32 v190, v196, v190
	v_mul_f32_e32 v191, v196, v191
	v_mul_f32_e32 v192, v196, v192
	v_mul_f32_e32 v193, v196, v193
	v_mul_f32_e32 v194, v196, v194
	v_mul_f32_e32 v195, v196, v195
	v_cvt_pk_bf16_f32 v188, v188, s77
	v_cvt_pk_bf16_f32 v189, v189, s77
	v_cvt_pk_bf16_f32 v190, v190, s77
	v_cvt_pk_bf16_f32 v191, v191, s77
	v_cvt_pk_bf16_f32 v192, v192, s77
	v_cvt_pk_bf16_f32 v193, v193, s77
	v_cvt_pk_bf16_f32 v194, v194, s77
	v_cvt_pk_bf16_f32 v195, v195, s77
	ds_write_b16 v198, v188
	ds_write_b16 v198, v189 offset:144
	ds_write_b16 v198, v190 offset:288
	ds_write_b16 v198, v191 offset:432
	ds_write_b16 v198, v192 offset:576
	ds_write_b16 v198, v193 offset:720
	ds_write_b16 v198, v194 offset:864
	ds_write_b16 v198, v195 offset:1008
	v_add_u32_e32 v197, 32, v51
	v_lshl_add_u32 v196, v197, 2, s96
	ds_read_b32 v196, v196 offset:40960
	v_lshrrev_b32_e32 v199, 3, v197
	v_and_b32_e32 v200, 7, v222
	v_xor_b32_e32 v199, v199, v200
	v_and_b32_e32 v200, 7, v197
	v_lshlrev_b32_e32 v200, 1, v200
	v_lshl_or_b32 v199, v199, 4, v200
	v_add_u32_e32 v198, v52, v199
	v_lshlrev_b32_e32 v188, 16, v130
	v_and_b32_e32 v189, 0xffff0000, v130
	v_lshlrev_b32_e32 v190, 16, v131
	v_and_b32_e32 v191, 0xffff0000, v131
	v_lshlrev_b32_e32 v192, 16, v132
	v_and_b32_e32 v193, 0xffff0000, v132
	v_lshlrev_b32_e32 v194, 16, v133
	v_and_b32_e32 v195, 0xffff0000, v133
	v_pk_fma_f32 v[204:205], v[140:141], v[188:189], v[224:225]
	v_pk_fma_f32 v[206:207], v[142:143], v[190:191], v[226:227]
	v_pk_fma_f32 v[208:209], v[144:145], v[192:193], v[228:229]
	v_pk_fma_f32 v[210:211], v[146:147], v[194:195], v[230:231]
	v_lshlrev_b32_e32 v188, 16, v134
	v_and_b32_e32 v189, 0xffff0000, v134
	v_lshlrev_b32_e32 v190, 16, v135
	v_and_b32_e32 v191, 0xffff0000, v135
	v_lshlrev_b32_e32 v192, 16, v136
	v_and_b32_e32 v193, 0xffff0000, v136
	v_lshlrev_b32_e32 v194, 16, v137
	v_and_b32_e32 v195, 0xffff0000, v137
	v_pk_fma_f32 v[204:205], v[148:149], v[188:189], v[204:205]
	v_pk_fma_f32 v[206:207], v[150:151], v[190:191], v[206:207]
	v_pk_fma_f32 v[208:209], v[152:153], v[192:193], v[208:209]
	v_pk_fma_f32 v[210:211], v[154:155], v[194:195], v[210:211]
	v_lshlrev_b32_e32 v188, 16, v172
	v_and_b32_e32 v189, 0xffff0000, v172
	v_lshlrev_b32_e32 v190, 16, v173
	v_and_b32_e32 v191, 0xffff0000, v173
	v_lshlrev_b32_e32 v192, 16, v174
	v_and_b32_e32 v193, 0xffff0000, v174
	v_lshlrev_b32_e32 v194, 16, v175
	v_and_b32_e32 v195, 0xffff0000, v175
	v_pk_fma_f32 v[204:205], v[156:157], v[188:189], v[204:205]
	v_pk_fma_f32 v[206:207], v[158:159], v[190:191], v[206:207]
	v_pk_fma_f32 v[208:209], v[160:161], v[192:193], v[208:209]
	v_pk_fma_f32 v[210:211], v[162:163], v[194:195], v[210:211]
	v_lshlrev_b32_e32 v188, 16, v176
	v_and_b32_e32 v189, 0xffff0000, v176
	v_lshlrev_b32_e32 v190, 16, v177
	v_and_b32_e32 v191, 0xffff0000, v177
	v_lshlrev_b32_e32 v192, 16, v178
	v_and_b32_e32 v193, 0xffff0000, v178
	v_lshlrev_b32_e32 v194, 16, v179
	v_and_b32_e32 v195, 0xffff0000, v179
	v_pk_fma_f32 v[204:205], v[164:165], v[188:189], v[204:205]
	v_pk_fma_f32 v[206:207], v[166:167], v[190:191], v[206:207]
	v_pk_fma_f32 v[208:209], v[168:169], v[192:193], v[208:209]
	v_pk_fma_f32 v[210:211], v[170:171], v[194:195], v[210:211]
	v_mul_f32_e32 v212, 0xbfb8aa3b, v204
	v_mul_f32_e32 v213, 0xbfb8aa3b, v205
	v_mul_f32_e32 v214, 0xbfb8aa3b, v206
	v_mul_f32_e32 v215, 0xbfb8aa3b, v207
	v_mul_f32_e32 v216, 0xbfb8aa3b, v208
	v_mul_f32_e32 v217, 0xbfb8aa3b, v209
	v_mul_f32_e32 v218, 0xbfb8aa3b, v210
	v_mul_f32_e32 v219, 0xbfb8aa3b, v211
	v_mul_f32_e32 v188, 0x3db504f3, v204
	v_mul_f32_e32 v189, 0x3db504f3, v205
	v_mul_f32_e32 v190, 0x3db504f3, v206
	v_mul_f32_e32 v191, 0x3db504f3, v207
	v_mul_f32_e32 v192, 0x3db504f3, v208
	v_mul_f32_e32 v193, 0x3db504f3, v209
	v_mul_f32_e32 v194, 0x3db504f3, v210
	v_mul_f32_e32 v195, 0x3db504f3, v211
	v_exp_f32_e32 v212, v212
	v_exp_f32_e32 v213, v213
	v_exp_f32_e32 v214, v214
	v_exp_f32_e32 v215, v215
	v_exp_f32_e32 v216, v216
	v_exp_f32_e32 v217, v217
	v_exp_f32_e32 v218, v218
	v_exp_f32_e32 v219, v219
	v_add_f32_e32 v212, 1.0, v212
	v_add_f32_e32 v213, 1.0, v213
	v_add_f32_e32 v214, 1.0, v214
	v_add_f32_e32 v215, 1.0, v215
	v_add_f32_e32 v216, 1.0, v216
	v_add_f32_e32 v217, 1.0, v217
	v_add_f32_e32 v218, 1.0, v218
	v_add_f32_e32 v219, 1.0, v219
	v_rcp_f32_e32 v212, v212
	v_rcp_f32_e32 v213, v213
	v_rcp_f32_e32 v214, v214
	v_rcp_f32_e32 v215, v215
	v_rcp_f32_e32 v216, v216
	v_rcp_f32_e32 v217, v217
	v_rcp_f32_e32 v218, v218
	v_rcp_f32_e32 v219, v219
	v_mul_f32_e32 v188, v188, v212
	v_mul_f32_e32 v189, v189, v213
	v_mul_f32_e32 v190, v190, v214
	v_mul_f32_e32 v191, v191, v215
	v_mul_f32_e32 v192, v192, v216
	v_mul_f32_e32 v193, v193, v217
	v_mul_f32_e32 v194, v194, v218
	v_mul_f32_e32 v195, v195, v219
	s_waitcnt lgkmcnt(0)
; #define MFMA(a, b, c) __builtin_amdgcn_mfma_f32_32x32x16_bf16((a), (b), (c), 0, 0, 0)
; DI u16 f2bf(float x) { return (u16)(pack2(x, 0.f) & 0xffffu); }
; DI f32x16 zero16() { f32x16 z; for (int i = 0; i < 16; ++i) z[i] = 0.f; return z; }
; DI uint2 pack4(const f32x16& a, int g) { uint2 o; o.x = pack2(a[4 * g], a[4 * g + 1]); o.y = pack2(a[4 * g + 2], a[4 * g + 3]); return o; }
; DI void mlstmA_item(const Params& p, char* lds, int item) {
;     ...
;     const float w = win[t];
; #pragma unroll
;     for (int e = 0; e < 8; ++e) KTs[(cgk * 8 + e) * 72 + t] = f2bf(a8[e] * w);
;   }
;   __syncthreads();
;   {
;     const int dt = wave >> 1;
; #pragma unroll
;     for (int x = 0; x < 2; ++x) {
;       const int e2 = (wave & 1) * 2 + x;
;       f32x16 acc = zero16();
; #pragma unroll
;       for (int ks = 0; ks < 4; ++ks) acc = MFMA(ldfrag(KTs + (dt * 32 + l31) * 72 + ks * 16 + 8 * hh), ldfrag(VTs + (e2 * 32 + l31) * 72 + ks * 16 + 8 * hh), acc);
; #pragma unroll
;       for (int g = 0; g < 4; ++g) *(uint2*)(KVS + (e2 * 32 + l31) * 128 + dt * 32 + 8 * g + 4 * hh) = pack4(acc, g);
;     }
	v_mul_f32_e32 v188, v196, v188
	v_mul_f32_e32 v189, v196, v189
	v_mul_f32_e32 v190, v196, v190
	v_mul_f32_e32 v191, v196, v191
	v_mul_f32_e32 v192, v196, v192
	v_mul_f32_e32 v193, v196, v193
	v_mul_f32_e32 v194, v196, v194
	v_mul_f32_e32 v195, v196, v195
	v_cvt_pk_bf16_f32 v188, v188, s77
	v_cvt_pk_bf16_f32 v189, v189, s77
	v_cvt_pk_bf16_f32 v190, v190, s77
	v_cvt_pk_bf16_f32 v191, v191, s77
	v_cvt_pk_bf16_f32 v192, v192, s77
	v_cvt_pk_bf16_f32 v193, v193, s77
	v_cvt_pk_bf16_f32 v194, v194, s77
	v_cvt_pk_bf16_f32 v195, v195, s77
	ds_write_b16 v198, v188
	ds_write_b16 v198, v189 offset:144
	ds_write_b16 v198, v190 offset:288
	ds_write_b16 v198, v191 offset:432
	ds_write_b16 v198, v192 offset:576
	ds_write_b16 v198, v193 offset:720
	ds_write_b16 v198, v194 offset:864
	ds_write_b16 v198, v195 offset:1008
	s_add_i32 s97, s10, s70
	v_and_b32_e32 v70, 15, v222
	s_bfe_u32 s72, s97, 0x20007
	v_lshlrev_b32_e32 v70, 3, v70
	s_lshl_b32 s72, s72, 7
	v_add_u32_e32 v70, s72, v70
	s_ashr_i32 s74, s97, 9
	s_ashr_i32 s75, s74, 31
	s_lshl_b64 s[74:75], s[74:75], 24
	s_add_u32 s74, s74, s4
	s_addc_u32 s75, s75, s5
	v_lshlrev_b32_e32 v76, 1, v70
	v_mov_b32_e32 v77, 0
	v_lshl_add_u64 v[78:79], s[74:75], 0, v[76:77]
	s_and_b32 s76, s97, 0x7f
	s_lshl_b32 s76, s76, 6
	v_lshrrev_b32_e32 v75, 4, v222
	s_movk_i32 s77, 0x800
	v_add_u32_e32 v184, s76, v75
	v_add_u32_e32 v185, -1, v184
	v_mov_b32_e32 v114, 0
	v_mov_b32_e32 v115, 0
	v_mov_b32_e32 v116, 0
	v_mov_b32_e32 v117, 0
	v_mov_b32_e32 v118, 0
	v_mov_b32_e32 v119, 0
	v_mov_b32_e32 v120, 0
	v_mov_b32_e32 v121, 0
	v_mov_b32_e32 v122, 0
	v_mov_b32_e32 v123, 0
	v_mov_b32_e32 v124, 0
	v_mov_b32_e32 v125, 0
	v_mad_i64_i32 v[186:187], s[88:89], v185, s77, v[78:79]
	v_cmp_lt_i32_e64 s[84:85], 2, v184
	s_and_saveexec_b64 s[86:87], s[84:85]
	global_load_dwordx4 v[114:117], v[186:187], off offset:-3072
	s_or_b64 exec, exec, s[86:87]
	v_cmp_lt_i32_e64 s[84:85], 1, v184
	s_and_saveexec_b64 s[86:87], s[84:85]
	global_load_dwordx4 v[118:121], v[186:187], off offset:-1024
	s_or_b64 exec, exec, s[86:87]
	v_cmp_lt_i32_e64 s[84:85], 0, v184
	s_and_saveexec_b64 s[86:87], s[84:85]
	global_load_dwordx4 v[122:125], v[186:187], off offset:1024
	s_or_b64 exec, exec, s[86:87]
	global_load_dwordx4 v[126:129], v[186:187], off offset:3072
	v_add_u32_e32 v184, 32, v184
	v_add_u32_e32 v185, -1, v184
	v_mov_b32_e32 v130, 0
	v_mov_b32_e32 v131, 0
	v_mov_b32_e32 v132, 0
	v_mov_b32_e32 v133, 0
	v_mov_b32_e32 v134, 0
	v_mov_b32_e32 v135, 0
	v_mov_b32_e32 v136, 0
	v_mov_b32_e32 v137, 0
	v_mov_b32_e32 v172, 0
	v_mov_b32_e32 v173, 0
	v_mov_b32_e32 v174, 0
	v_mov_b32_e32 v175, 0
	v_mad_i64_i32 v[186:187], s[88:89], v185, s77, v[78:79]
	v_cmp_lt_i32_e64 s[84:85], 2, v184
	s_and_saveexec_b64 s[86:87], s[84:85]
	global_load_dwordx4 v[130:133], v[186:187], off offset:-3072
	s_or_b64 exec, exec, s[86:87]
	v_cmp_lt_i32_e64 s[84:85], 1, v184
	s_and_saveexec_b64 s[86:87], s[84:85]
	global_load_dwordx4 v[134:137], v[186:187], off offset:-1024
	s_or_b64 exec, exec, s[86:87]
	v_cmp_lt_i32_e64 s[84:85], 0, v184
	s_and_saveexec_b64 s[86:87], s[84:85]
	global_load_dwordx4 v[172:175], v[186:187], off offset:1024
	s_or_b64 exec, exec, s[86:87]
	global_load_dwordx4 v[176:179], v[186:187], off offset:3072
.LBB0_340:
	s_lshl_b64 s[0:1], s[10:11], 15
	v_lshrrev_b32_e32 v0, 5, v18
	v_ashrrev_i32_e32 v2, 2, v18
	v_lshrrev_b32_e32 v1, 5, v19
	s_add_u32 s0, s2, s0
	v_and_b32_e32 v31, 2, v0
	v_and_b32_e32 v0, 0xffffffe0, v2
	s_addc_u32 s1, s16, s1
	s_movk_i32 s8, 0xffe0
	v_lshlrev_b32_e32 v16, 3, v1
	v_lshl_add_u32 v30, v1, 4, 0
	v_ashrrev_i32_e32 v1, 31, v0
	v_and_b32_e32 v19, 31, v18
	v_bfi_b32 v2, s8, v2, v18
	v_lshl_add_u64 v[0:1], v[0:1], 1, s[0:1]
	v_mad_u64_u32 v[58:59], s[12:13], v2, s26, v[30:31]
	v_bfe_u32 v70, v2, 3, 3
	v_lshrrev_b32_e32 v71, 4, v30
	v_sub_u32_e32 v72, v58, v30
	v_or_b32_e32 v73, 0, v71
	v_xor_b32_e32 v73, v73, v70
	v_lshl_add_u32 v74, v73, 4, v72
	v_or_b32_e32 v73, 2, v71
	v_xor_b32_e32 v73, v73, v70
	v_lshl_add_u32 v75, v73, 4, v72
	v_or_b32_e32 v73, 4, v71
	v_xor_b32_e32 v73, v73, v70
	v_lshl_add_u32 v76, v73, 4, v72
	v_or_b32_e32 v73, 6, v71
	v_xor_b32_e32 v73, v73, v70
	v_lshl_add_u32 v77, v73, 4, v72
	v_lshl_add_u64 v[20:21], v[0:1], 0, v[16:17]
	v_lshl_or_b32 v0, v31, 5, v19
	s_waitcnt lgkmcnt(0)
	s_barrier
	v_mad_u32_u24 v16, v0, s26, v30
	ds_read_b128 v[22:25], v74
	ds_read_b128 v[26:29], v75
	ds_read_b128 v[0:3], v16 offset:18432
	ds_read_b128 v[50:53], v16 offset:18464
	s_waitcnt lgkmcnt(1)
	v_mfma_f32_32x32x16_bf16 v[0:15], v[22:25], v[0:3], 0
	v_lshlrev_b32_e32 v62, 8, v19
	s_movk_i32 s0, 0x80
	v_cmp_gt_i32_e32 vcc, s0, v18
	s_waitcnt lgkmcnt(0)
	v_mfma_f32_32x32x16_bf16 v[0:15], v[26:29], v[50:53], v[0:15]
	ds_read_b128 v[50:53], v76
	ds_read_b128 v[54:57], v16 offset:18496
	s_waitcnt lgkmcnt(0)
	v_mfma_f32_32x32x16_bf16 v[0:15], v[50:53], v[54:57], v[0:15]
	ds_read_b128 v[54:57], v77
	ds_read_b128 v[58:61], v16 offset:18528
	v_lshl_or_b32 v16, v31, 13, v62
	s_waitcnt lgkmcnt(0)
	v_mfma_f32_32x32x16_bf16 v[0:15], v[54:57], v[58:61], v[0:15]
	v_lshl_add_u64 v[58:59], v[20:21], 0, v[16:17]
	v_or_b32_e32 v16, 1, v31
	s_nop 9
	v_cvt_pk_bf16_f32 v0, v0, v1
	v_cvt_pk_bf16_f32 v1, v2, v3
	global_store_dwordx2 v[58:59], v[0:1], off
	v_cvt_pk_bf16_f32 v0, v4, v5
	v_cvt_pk_bf16_f32 v1, v6, v7
	global_store_dwordx2 v[58:59], v[0:1], off offset:16
	v_cvt_pk_bf16_f32 v0, v8, v9
	v_cvt_pk_bf16_f32 v1, v10, v11
	global_store_dwordx2 v[58:59], v[0:1], off offset:32
	v_cvt_pk_bf16_f32 v0, v12, v13
	v_cvt_pk_bf16_f32 v1, v14, v15
	global_store_dwordx2 v[58:59], v[0:1], off offset:48
	v_lshl_or_b32 v0, v16, 5, v19
	v_mad_u32_u24 v19, v0, s26, v30
	ds_read_b128 v[0:3], v19 offset:18432
	ds_read_b128 v[58:61], v19 offset:18464
	s_waitcnt lgkmcnt(1)
	v_mfma_f32_32x32x16_bf16 v[0:15], v[22:25], v[0:3], 0
	ds_read_b128 v[22:25], v19 offset:18496
	v_lshl_or_b32 v16, v16, 13, v62
	v_lshl_add_u64 v[20:21], v[20:21], 0, v[16:17]
	s_waitcnt lgkmcnt(1)
	v_mfma_f32_32x32x16_bf16 v[0:15], v[26:29], v[58:61], v[0:15]
	s_waitcnt lgkmcnt(0)
	v_mfma_f32_32x32x16_bf16 v[0:15], v[50:53], v[22:25], v[0:15]
	ds_read_b128 v[22:25], v19 offset:18528
	s_waitcnt lgkmcnt(0)
	v_mfma_f32_32x32x16_bf16 v[0:15], v[54:57], v[22:25], v[0:15]
	s_nop 11
	v_cvt_pk_bf16_f32 v0, v0, v1
	v_cvt_pk_bf16_f32 v1, v2, v3
	global_store_dwordx2 v[20:21], v[0:1], off
	v_cvt_pk_bf16_f32 v0, v4, v5
	v_cvt_pk_bf16_f32 v1, v6, v7
	global_store_dwordx2 v[20:21], v[0:1], off offset:16
	v_cvt_pk_bf16_f32 v0, v8, v9
	v_cvt_pk_bf16_f32 v1, v10, v11
	global_store_dwordx2 v[20:21], v[0:1], off offset:32
	v_cvt_pk_bf16_f32 v0, v12, v13
	v_cvt_pk_bf16_f32 v1, v14, v15
	global_store_dwordx2 v[20:21], v[0:1], off offset:48
	s_and_saveexec_b64 s[0:1], vcc
	s_cbranch_execz .LBB0_323
; DI void mlstmA_item(const Params& p, char* lds, int item) {
;     ...
;     if (tid < 128) {
;       float sacc = 0.f;
;       for (int s8 = 0; s8 < 8; ++s8) { const uint4 raw = *(const uint4*)(KTs + tid * 72 + s8 * 8); float x8[8]; unpack8(raw, x8); for (int e = 0; e < 8; ++e) sacc += x8[e]; }
;       KSUM[tid] = sacc;
;     }
	v_mul_lo_u32 v0, v18, s26
	v_add_u32_e32 v16, 0, v0
	ds_read_b128 v[0:3], v240
	v_xor_b32_e32 v79, 0, v78
	v_lshl_add_u32 v240, v79, 4, v16
	v_xor_b32_e32 v79, 1, v78
	v_lshl_add_u32 v241, v79, 4, v16
	v_xor_b32_e32 v79, 2, v78
	v_lshl_add_u32 v242, v79, 4, v16
	v_xor_b32_e32 v79, 3, v78
	v_lshl_add_u32 v243, v79, 4, v16
	v_xor_b32_e32 v79, 4, v78
	v_lshl_add_u32 v244, v79, 4, v16
	v_xor_b32_e32 v79, 5, v78
	v_lshl_add_u32 v245, v79, 4, v16
	v_xor_b32_e32 v79, 6, v78
	v_lshl_add_u32 v246, v79, 4, v16
	v_xor_b32_e32 v79, 7, v78
	v_lshl_add_u32 v247, v79, 4, v16
	ds_read_b128 v[0:3], v16
	ds_read_b128 v[4:7], v241
	ds_read_b128 v[8:11], v242
	ds_read_b128 v[12:15], v243
	s_lshl_b64 s[12:13], s[10:11], 9
	s_add_u32 s12, s17, s12
	s_addc_u32 s13, s20, s13
	s_waitcnt lgkmcnt(3)
	v_lshlrev_b32_e32 v19, 16, v0
	v_and_b32_e32 v0, 0xffff0000, v0
	v_add_f32_e32 v19, 0, v19
	v_lshlrev_b32_e32 v20, 16, v1
	v_add_f32_e32 v0, v19, v0
	v_and_b32_e32 v1, 0xffff0000, v1
	v_add_f32_e32 v0, v0, v20
	v_lshlrev_b32_e32 v21, 16, v2
	v_add_f32_e32 v0, v0, v1
	v_and_b32_e32 v2, 0xffff0000, v2
	v_add_f32_e32 v0, v0, v21
	v_lshlrev_b32_e32 v22, 16, v3
	v_add_f32_e32 v0, v0, v2
	v_and_b32_e32 v3, 0xffff0000, v3
	v_add_f32_e32 v0, v0, v22
	v_add_f32_e32 v0, v0, v3
	s_waitcnt lgkmcnt(2)
	v_lshlrev_b32_e32 v1, 16, v4
	v_and_b32_e32 v2, 0xffff0000, v4
	v_add_f32_e32 v0, v0, v1
	v_lshlrev_b32_e32 v3, 16, v5
	v_add_f32_e32 v0, v0, v2
	v_and_b32_e32 v4, 0xffff0000, v5
	v_add_f32_e32 v0, v0, v3
	v_lshlrev_b32_e32 v5, 16, v6
	v_add_f32_e32 v0, v0, v4
	v_and_b32_e32 v6, 0xffff0000, v6
	v_add_f32_e32 v0, v0, v5
	v_lshlrev_b32_e32 v19, 16, v7
	v_add_f32_e32 v0, v0, v6
	v_and_b32_e32 v7, 0xffff0000, v7
	v_add_f32_e32 v0, v0, v19
	v_add_f32_e32 v0, v0, v7
	s_waitcnt lgkmcnt(1)
	v_lshlrev_b32_e32 v1, 16, v8
	v_and_b32_e32 v2, 0xffff0000, v8
	v_add_f32_e32 v0, v0, v1
	v_lshlrev_b32_e32 v3, 16, v9
	v_add_f32_e32 v0, v0, v2
	v_and_b32_e32 v4, 0xffff0000, v9
	v_add_f32_e32 v0, v0, v3
	v_lshlrev_b32_e32 v5, 16, v10
	v_add_f32_e32 v0, v0, v4
	v_and_b32_e32 v6, 0xffff0000, v10
	v_add_f32_e32 v0, v0, v5
	v_lshlrev_b32_e32 v7, 16, v11
	v_add_f32_e32 v0, v0, v6
	v_and_b32_e32 v8, 0xffff0000, v11
	v_add_f32_e32 v0, v0, v7
	v_add_f32_e32 v0, v0, v8
	s_waitcnt lgkmcnt(0)
	v_lshlrev_b32_e32 v1, 16, v12
	v_and_b32_e32 v2, 0xffff0000, v12
	v_add_f32_e32 v0, v0, v1
	v_lshlrev_b32_e32 v3, 16, v13
	v_add_f32_e32 v0, v0, v2
	v_and_b32_e32 v4, 0xffff0000, v13
	v_add_f32_e32 v0, v0, v3
	v_lshlrev_b32_e32 v5, 16, v14
	v_add_f32_e32 v0, v0, v4
	v_add_f32_e32 v4, v0, v5
	ds_read_b128 v[0:3], v244
	v_and_b32_e32 v6, 0xffff0000, v14
	v_lshlrev_b32_e32 v7, 16, v15
	v_add_f32_e32 v4, v4, v6
	v_and_b32_e32 v8, 0xffff0000, v15
	v_add_f32_e32 v4, v4, v7
	v_add_f32_e32 v8, v4, v8
	ds_read_b128 v[4:7], v245
	s_waitcnt lgkmcnt(1)
	v_lshlrev_b32_e32 v9, 16, v0
	v_and_b32_e32 v0, 0xffff0000, v0
	v_add_f32_e32 v8, v8, v9
	v_lshlrev_b32_e32 v10, 16, v1
	v_add_f32_e32 v0, v8, v0
	v_and_b32_e32 v1, 0xffff0000, v1
	v_add_f32_e32 v0, v0, v10
	v_lshlrev_b32_e32 v11, 16, v2
	v_add_f32_e32 v0, v0, v1
	v_and_b32_e32 v2, 0xffff0000, v2
	v_add_f32_e32 v0, v0, v11
	v_lshlrev_b32_e32 v12, 16, v3
	v_add_f32_e32 v0, v0, v2
	v_and_b32_e32 v3, 0xffff0000, v3
	v_add_f32_e32 v0, v0, v12
	v_add_f32_e32 v0, v0, v3
	s_waitcnt lgkmcnt(0)
	v_lshlrev_b32_e32 v1, 16, v4
	v_and_b32_e32 v2, 0xffff0000, v4
	v_add_f32_e32 v0, v0, v1
	v_lshlrev_b32_e32 v3, 16, v5
	v_add_f32_e32 v0, v0, v2
	v_and_b32_e32 v4, 0xffff0000, v5
	v_add_f32_e32 v0, v0, v3
	v_lshlrev_b32_e32 v5, 16, v6
	v_add_f32_e32 v0, v0, v4
	v_add_f32_e32 v4, v0, v5
	ds_read_b128 v[0:3], v246
	v_and_b32_e32 v6, 0xffff0000, v6
	v_lshlrev_b32_e32 v8, 16, v7
	v_add_f32_e32 v4, v4, v6
	v_and_b32_e32 v7, 0xffff0000, v7
	v_add_f32_e32 v4, v4, v8
	v_add_f32_e32 v8, v4, v7
	ds_read_b128 v[4:7], v247
	s_waitcnt lgkmcnt(1)
	v_lshlrev_b32_e32 v9, 16, v0
	v_and_b32_e32 v0, 0xffff0000, v0
	v_add_f32_e32 v8, v8, v9
	v_lshlrev_b32_e32 v10, 16, v1
	v_add_f32_e32 v0, v8, v0
	v_and_b32_e32 v1, 0xffff0000, v1
	v_add_f32_e32 v0, v0, v10
	v_lshlrev_b32_e32 v11, 16, v2
	v_add_f32_e32 v0, v0, v1
	v_and_b32_e32 v2, 0xffff0000, v2
	v_add_f32_e32 v0, v0, v11
	v_lshlrev_b32_e32 v12, 16, v3
	v_add_f32_e32 v0, v0, v2
	v_and_b32_e32 v3, 0xffff0000, v3
	v_add_f32_e32 v0, v0, v12
	v_add_f32_e32 v0, v0, v3
	s_waitcnt lgkmcnt(0)
	v_lshlrev_b32_e32 v1, 16, v4
	v_and_b32_e32 v2, 0xffff0000, v4
	v_add_f32_e32 v0, v0, v1
	v_lshlrev_b32_e32 v3, 16, v5
	v_add_f32_e32 v0, v0, v2
	v_and_b32_e32 v4, 0xffff0000, v5
	v_add_f32_e32 v0, v0, v3
	v_lshlrev_b32_e32 v5, 16, v6
	v_add_f32_e32 v0, v0, v4
	v_and_b32_e32 v6, 0xffff0000, v6
	v_add_f32_e32 v0, v0, v5
	v_lshlrev_b32_e32 v8, 16, v7
	v_add_f32_e32 v0, v0, v6
	v_and_b32_e32 v7, 0xffff0000, v7
	v_add_f32_e32 v0, v0, v8
	v_ashrrev_i32_e32 v19, 31, v18
	v_add_f32_e32 v2, v0, v7
	v_lshl_add_u64 v[0:1], v[18:19], 2, s[12:13]
	global_store_dword v[0:1], v2, off
	s_branch .LBB0_323
